# spatial-gating LayerNorm: the two quad-wide shuffle-adds use DPP quad_perm adds instead of ds_bpermute round trips
# baseline (speedup 1.0000x reference)
; __device__ __forceinline__ void sg_unit(LAS unsigned char* lds, const bf16_t* P0, bf16_t* MIX, const float* lng, const float* lnb, const float* wsp, const float* bsp, int b, int nch, int g) {
;     ...
;     const size_t rowbase = (size_t)b * SEQ + (size_t)nch * 128;
;     __syncthreads();
;     {
;         const int s = tid >> 2, part = tid & 3;
;         const bf16_t* vp = P0 + (rowbase + s) * AB_IN + 512 + 128 * g + 32 * part;
;         float x[32]; float sum = 0.f;
; #pragma unroll
;         for (int j = 0; j < 4; ++j) { const u32x4 wv = *(const u32x4*)(vp + 8 * j);
;             x[8 * j + 0] = bflo(wv.x); x[8 * j + 1] = bfhi(wv.x); x[8 * j + 2] = bflo(wv.y); x[8 * j + 3] = bfhi(wv.y);
;             x[8 * j + 4] = bflo(wv.z); x[8 * j + 5] = bfhi(wv.z); x[8 * j + 6] = bflo(wv.w); x[8 * j + 7] = bfhi(wv.w); }
; #pragma unroll
;         for (int j = 0; j < 32; ++j) sum += x[j];
;         sum += __shfl_xor(sum, 1); sum += __shfl_xor(sum, 2);
;         const float mean = sum * (1.f / 128.f); float q = 0.f;
; #pragma unroll
;         for (int j = 0; j < 32; ++j) { x[j] -= mean; q += x[j] * x[j]; }
;         q += __shfl_xor(q, 1); q += __shfl_xor(q, 2);
;         const float rstd = __builtin_amdgcn_rsqf(q * (1.f / 128.f) + LN_EPS);
.LBB0_290:
	s_cmpk_gt_i32 s33, 0x7ff
	s_mov_b64 s[0:1], -1
	s_cbranch_scc0 .LBB0_294
	s_lshl_b32 s1, s33, 5
	s_and_b32 s5, s1, 0x7fffff80
	s_add_i32 s5, s5, 0xffff0000
	v_add_u32_e32 v0, s5, v81
	s_and_b32 s0, s33, 3
	v_mul_lo_u32 v72, v0, s3
	v_lshl_add_u64 v[0:1], s[26:27], 0, v[72:73]
	s_lshl_b32 s22, s0, 8
	v_lshl_add_u64 v[0:1], v[0:1], 0, s[22:23]
	v_mov_b32_e32 v91, v73
	s_waitcnt vmcnt(7)
	v_lshl_add_u64 v[12:13], v[0:1], 0, v[90:91]
	s_barrier
	global_load_dwordx4 v[0:3], v[12:13], off offset:1072
	global_load_dwordx4 v[4:7], v[12:13], off offset:1056
	global_load_dwordx4 v[8:11], v[12:13], off offset:1040
	s_nop 0
	global_load_dwordx4 v[12:15], v[12:13], off offset:1024
	v_cmp_lt_i32_e32 vcc, v113, v114
	s_lshl_b32 s22, s0, 9
	v_lshl_add_u64 v[148:149], v[74:75], 0, s[22:23]
	v_lshl_add_u64 v[218:219], v[76:77], 0, s[22:23]
	global_load_dwordx4 v[150:153], v[148:149], off offset:16
	global_load_dwordx4 v[154:157], v[148:149], off
	global_load_dwordx4 v[158:161], v[218:219], off offset:16
	global_load_dwordx4 v[162:165], v[218:219], off
	global_load_dwordx4 v[166:169], v[148:149], off offset:48
	global_load_dwordx4 v[170:173], v[148:149], off offset:32
	global_load_dwordx4 v[178:181], v[218:219], off offset:48
	global_load_dwordx4 v[182:185], v[218:219], off offset:32
	global_load_dwordx4 v[186:189], v[148:149], off offset:80
	global_load_dwordx4 v[190:193], v[148:149], off offset:64
	global_load_dwordx4 v[194:197], v[218:219], off offset:80
	global_load_dwordx4 v[198:201], v[218:219], off offset:64
	global_load_dwordx4 v[202:205], v[148:149], off offset:112
	global_load_dwordx4 v[206:209], v[148:149], off offset:96
	global_load_dwordx4 v[210:213], v[218:219], off offset:112
	global_load_dwordx4 v[214:217], v[218:219], off offset:96
	s_lshl_b32 s4, s0, 7
	s_lshl_b32 s0, s0, 14
	v_add_lshl_u32 v72, s0, v83, 2
	v_readlane_b32 s0, v254, 18
	v_readlane_b32 s1, v254, 19
	s_waitcnt vmcnt(18)
	v_lshlrev_b32_e32 v24, 16, v4
	s_waitcnt vmcnt(17)
	v_lshlrev_b32_e32 v32, 16, v8
	s_waitcnt vmcnt(16)
	v_lshlrev_b32_e32 v40, 16, v12
	v_and_b32_e32 v39, 0xffff0000, v12
	v_lshlrev_b32_e32 v36, 16, v14
	v_and_b32_e32 v35, 0xffff0000, v14
	v_lshlrev_b32_e32 v34, 16, v15
	v_and_b32_e32 v33, 0xffff0000, v15
	v_lshlrev_b32_e32 v15, 16, v0
	v_and_b32_e32 v14, 0xffff0000, v0
	v_add_f32_e32 v0, 0, v40
	v_lshlrev_b32_e32 v38, 16, v13
	v_add_f32_e32 v0, v0, v39
	v_and_b32_e32 v37, 0xffff0000, v13
	v_add_f32_e32 v0, v0, v38
	v_add_f32_e32 v0, v0, v37
	v_add_f32_e32 v0, v0, v36
	v_add_f32_e32 v0, v0, v35
	v_add_f32_e32 v0, v0, v34
	v_add_f32_e32 v0, v0, v33
	v_and_b32_e32 v31, 0xffff0000, v8
	v_add_f32_e32 v0, v0, v32
	v_lshlrev_b32_e32 v30, 16, v9
	v_add_f32_e32 v0, v0, v31
	v_and_b32_e32 v29, 0xffff0000, v9
	v_add_f32_e32 v0, v0, v30
	v_lshlrev_b32_e32 v28, 16, v10
	v_add_f32_e32 v0, v0, v29
	v_and_b32_e32 v27, 0xffff0000, v10
	v_add_f32_e32 v0, v0, v28
	v_lshlrev_b32_e32 v26, 16, v11
	v_add_f32_e32 v0, v0, v27
	v_and_b32_e32 v25, 0xffff0000, v11
	v_add_f32_e32 v0, v0, v26
	v_add_f32_e32 v0, v0, v25
	v_and_b32_e32 v22, 0xffff0000, v4
	v_add_f32_e32 v0, v0, v24
	v_lshlrev_b32_e32 v21, 16, v5
	v_add_f32_e32 v0, v0, v22
	v_and_b32_e32 v20, 0xffff0000, v5
	v_add_f32_e32 v0, v0, v21
	v_lshlrev_b32_e32 v19, 16, v6
	v_add_f32_e32 v0, v0, v20
	v_and_b32_e32 v18, 0xffff0000, v6
	v_add_f32_e32 v0, v0, v19
	v_lshlrev_b32_e32 v17, 16, v7
	v_add_f32_e32 v0, v0, v18
	v_and_b32_e32 v16, 0xffff0000, v7
	v_add_f32_e32 v0, v0, v17
	v_add_f32_e32 v0, v0, v16
	v_add_f32_e32 v0, v0, v15
	v_lshlrev_b32_e32 v13, 16, v1
	v_add_f32_e32 v0, v0, v14
	v_and_b32_e32 v12, 0xffff0000, v1
	v_add_f32_e32 v0, v0, v13
	v_lshlrev_b32_e32 v11, 16, v2
	v_add_f32_e32 v0, v0, v12
	v_and_b32_e32 v10, 0xffff0000, v2
	v_add_f32_e32 v0, v0, v11
	v_add_f32_e32 v2, v0, v10
	v_cndmask_b32_e32 v0, v112, v113, vcc
	v_cmp_lt_i32_e32 vcc, v115, v114
	v_lshlrev_b32_e32 v6, 2, v0
	v_lshlrev_b32_e32 v1, 16, v3
	v_cndmask_b32_e32 v0, v112, v115, vcc
	v_lshlrev_b32_e32 v7, 2, v0
	v_and_b32_e32 v0, 0xffff0000, v3
	v_add_f32_e32 v2, v2, v1
	v_add_f32_e32 v2, v2, v0
	s_nop 1
	v_add_f32_dpp v2, v2, v2 quad_perm:[1,0,3,2] row_mask:0xf bank_mask:0xf
	s_nop 1
	v_add_f32_dpp v3, v2, v2 quad_perm:[2,3,0,1] row_mask:0xf bank_mask:0xf
	v_fmac_f32_e32 v39, 0xbc000000, v3
	v_fmac_f32_e32 v40, 0xbc000000, v3
	v_mul_f32_e32 v8, v39, v39
	v_fmac_f32_e32 v8, v40, v40
	v_fmac_f32_e32 v38, 0xbc000000, v3
	v_fmac_f32_e32 v8, v38, v38
	v_fmac_f32_e32 v37, 0xbc000000, v3
	v_fmac_f32_e32 v8, v37, v37
	v_fmac_f32_e32 v36, 0xbc000000, v3
	v_fmac_f32_e32 v8, v36, v36
	v_fmac_f32_e32 v35, 0xbc000000, v3
	v_fmac_f32_e32 v8, v35, v35
	v_fmac_f32_e32 v34, 0xbc000000, v3
	v_fmac_f32_e32 v8, v34, v34
	v_fmac_f32_e32 v33, 0xbc000000, v3
	v_fmac_f32_e32 v8, v33, v33
	v_fmac_f32_e32 v32, 0xbc000000, v3
	v_fmac_f32_e32 v8, v32, v32
	v_fmac_f32_e32 v31, 0xbc000000, v3
	v_fmac_f32_e32 v8, v31, v31
	v_fmac_f32_e32 v30, 0xbc000000, v3
	v_fmac_f32_e32 v8, v30, v30
	v_fmac_f32_e32 v29, 0xbc000000, v3
	v_fmac_f32_e32 v8, v29, v29
	v_fmac_f32_e32 v28, 0xbc000000, v3
	v_fmac_f32_e32 v8, v28, v28
	v_fmac_f32_e32 v27, 0xbc000000, v3
	v_fmac_f32_e32 v8, v27, v27
	v_fmac_f32_e32 v26, 0xbc000000, v3
	v_fmac_f32_e32 v8, v26, v26
	v_fmac_f32_e32 v25, 0xbc000000, v3
	v_fmac_f32_e32 v8, v25, v25
	v_fmac_f32_e32 v24, 0xbc000000, v3
	v_fmac_f32_e32 v8, v24, v24
	v_fmac_f32_e32 v22, 0xbc000000, v3
	v_fmac_f32_e32 v8, v22, v22
	v_fmac_f32_e32 v21, 0xbc000000, v3
	v_fmac_f32_e32 v8, v21, v21
	v_fmac_f32_e32 v20, 0xbc000000, v3
	v_fmac_f32_e32 v8, v20, v20
	v_fmac_f32_e32 v19, 0xbc000000, v3
	v_fmac_f32_e32 v8, v19, v19
	v_fmac_f32_e32 v18, 0xbc000000, v3
	v_fmac_f32_e32 v8, v18, v18
	v_fmac_f32_e32 v17, 0xbc000000, v3
	v_fmac_f32_e32 v8, v17, v17
	v_fmac_f32_e32 v16, 0xbc000000, v3
	v_fmac_f32_e32 v8, v16, v16
	v_fmac_f32_e32 v15, 0xbc000000, v3
	v_fmac_f32_e32 v8, v15, v15
	v_fmac_f32_e32 v14, 0xbc000000, v3
	v_fmac_f32_e32 v8, v14, v14
	v_fmac_f32_e32 v13, 0xbc000000, v3
	v_fmac_f32_e32 v8, v13, v13
	v_fmac_f32_e32 v12, 0xbc000000, v3
	v_mul_f32_e32 v2, 0x3c000000, v3
	v_fmac_f32_e32 v8, v12, v12
	v_fmac_f32_e32 v11, 0xbc000000, v3
	v_fmac_f32_e32 v8, v11, v11
	v_fmac_f32_e32 v10, 0xbc000000, v3
	v_pk_add_f32 v[4:5], v[0:1], v[2:3] op_sel_hi:[1,0] neg_lo:[0,1] neg_hi:[0,1]
	v_fmac_f32_e32 v8, v10, v10
	v_pk_mul_f32 v[0:1], v[4:5], v[4:5]
	s_nop 0
	v_add_f32_e32 v1, v1, v8
	v_add_f32_e32 v0, v0, v1
	s_nop 1
	v_add_f32_dpp v0, v0, v0 quad_perm:[1,0,3,2] row_mask:0xf bank_mask:0xf
	v_lshl_add_u64 v[8:9], v[74:75], 0, s[22:23]
	v_lshl_add_u64 v[6:7], v[76:77], 0, s[22:23]
	v_add_f32_dpp v0, v0, v0 quad_perm:[2,3,0,1] row_mask:0xf bank_mask:0xf
	v_fmamk_f32 v0, v0, 0x3c000000, v106
	v_rsq_f32_e32 v23, v0
	s_nop 0
	v_mul_f32_e32 v52, v40, v23
	s_waitcnt vmcnt(0)
; #define LAS __attribute__((address_space(3)))
; __device__ __forceinline__ unsigned pk2(float lo, float hi) { unsigned r; asm("v_cvt_pk_bf16_f32 %0, %1, %2" : "=v"(r) : "v"(lo), "v"(hi)); return r; }
; __device__ __forceinline__ void sg_unit(LAS unsigned char* lds, const bf16_t* P0, bf16_t* MIX, const float* lng, const float* lnb, const float* wsp, const float* bsp, int b, int nch, int g) {
;     ...
;         const float* gp = lng + 128 * g + 32 * part; const float* bp = lnb + 128 * g + 32 * part;
; #pragma unroll
;         for (int j = 0; j < 4; ++j) { float y[8];
; #pragma unroll
;             for (int e = 0; e < 8; ++e) y[e] = x[8 * j + e] * rstd * gp[8 * j + e] + bp[8 * j + e];
;             *(LAS u32x4*)(vnl + s * 136 + 32 * part + 8 * j) = (u32x4){pk2(y[0], y[1]), pk2(y[2], y[3]), pk2(y[4], y[5]), pk2(y[6], y[7])}; }
	v_mov_b32_e32 v0, v150
	v_mov_b32_e32 v1, v151
	v_mov_b32_e32 v2, v152
	v_mov_b32_e32 v3, v153
	v_mov_b32_e32 v40, v154
	v_mov_b32_e32 v41, v155
	v_mov_b32_e32 v42, v156
	v_mov_b32_e32 v43, v157
	v_mov_b32_e32 v44, v158
	v_mov_b32_e32 v45, v159
	v_mov_b32_e32 v46, v160
	v_mov_b32_e32 v47, v161
	v_mov_b32_e32 v48, v162
	v_mov_b32_e32 v49, v163
	v_mov_b32_e32 v50, v164
	v_mov_b32_e32 v51, v165
	v_mul_f32_e32 v36, v36, v23
	v_mul_f32_e32 v39, v39, v23
	v_mul_f32_e32 v38, v38, v23
	v_mul_f32_e32 v37, v37, v23
	v_mul_f32_e32 v28, v28, v23
	v_mul_f32_e32 v31, v31, v23
	v_mul_f32_e32 v30, v30, v23
	v_mul_f32_e32 v29, v29, v23
	v_mul_f32_e32 v19, v19, v23
	v_mul_f32_e32 v22, v22, v23
	v_mul_f32_e32 v21, v21, v23
	v_mul_f32_e32 v20, v20, v23
	v_mul_f32_e32 v11, v11, v23
	v_mul_f32_e32 v15, v15, v23
	v_mul_f32_e32 v14, v14, v23
	v_mul_f32_e32 v13, v13, v23
	v_mul_f32_e32 v12, v12, v23
	s_waitcnt vmcnt(1)
	v_fma_f32 v36, v0, v36, v44
	v_mul_f32_e32 v0, v35, v23
	v_fma_f32 v35, v1, v0, v45
	v_mul_f32_e32 v0, v34, v23
	v_fma_f32 v34, v2, v0, v46
	v_mul_f32_e32 v0, v33, v23
	s_waitcnt vmcnt(0)
	v_fma_f32 v40, v40, v52, v48
	v_fma_f32 v39, v41, v39, v49
	v_fma_f32 v38, v42, v38, v50
	v_fmac_f32_e32 v51, v43, v37
	v_fmac_f32_e32 v47, v3, v0
	v_cvt_pk_bf16_f32 v0, v40, v39
	v_cvt_pk_bf16_f32 v1, v38, v51
	v_cvt_pk_bf16_f32 v2, v36, v35
	v_cvt_pk_bf16_f32 v3, v34, v47
	ds_write_b128 v107, v[0:3]
	v_mul_f32_e32 v44, v32, v23
	v_mov_b32_e32 v0, v166
	v_mov_b32_e32 v1, v167
	v_mov_b32_e32 v2, v168
	v_mov_b32_e32 v3, v169
	v_mov_b32_e32 v32, v170
	v_mov_b32_e32 v33, v171
	v_mov_b32_e32 v34, v172
	v_mov_b32_e32 v35, v173
	v_mov_b32_e32 v36, v178
	v_mov_b32_e32 v37, v179
	v_mov_b32_e32 v38, v180
	v_mov_b32_e32 v39, v181
	v_mov_b32_e32 v40, v182
	v_mov_b32_e32 v41, v183
	v_mov_b32_e32 v42, v184
	v_mov_b32_e32 v43, v185
	s_waitcnt vmcnt(1)
	v_fma_f32 v28, v0, v28, v36
	v_mul_f32_e32 v0, v27, v23
	v_fma_f32 v27, v1, v0, v37
	v_mul_f32_e32 v0, v26, v23
	v_fma_f32 v26, v2, v0, v38
	v_mul_f32_e32 v0, v25, v23
	s_waitcnt vmcnt(0)
	v_fma_f32 v32, v32, v44, v40
	v_fma_f32 v31, v33, v31, v41
	v_fma_f32 v30, v34, v30, v42
	v_fmac_f32_e32 v43, v35, v29
	v_fmac_f32_e32 v39, v3, v0
	v_cvt_pk_bf16_f32 v0, v32, v31
	v_cvt_pk_bf16_f32 v1, v30, v43
	v_cvt_pk_bf16_f32 v2, v28, v27
	v_cvt_pk_bf16_f32 v3, v26, v39
	ds_write_b128 v107, v[0:3] offset:16
	v_mul_f32_e32 v36, v24, v23
	v_mov_b32_e32 v0, v186
	v_mov_b32_e32 v1, v187
	v_mov_b32_e32 v2, v188
	v_mov_b32_e32 v3, v189
	v_mov_b32_e32 v24, v190
	v_mov_b32_e32 v25, v191
	v_mov_b32_e32 v26, v192
	v_mov_b32_e32 v27, v193
	v_mov_b32_e32 v28, v194
	v_mov_b32_e32 v29, v195
	v_mov_b32_e32 v30, v196
	v_mov_b32_e32 v31, v197
	v_mov_b32_e32 v32, v198
	v_mov_b32_e32 v33, v199
	v_mov_b32_e32 v34, v200
	v_mov_b32_e32 v35, v201
	s_waitcnt vmcnt(1)
	v_fma_f32 v19, v0, v19, v28
	v_mul_f32_e32 v0, v18, v23
	v_fma_f32 v18, v1, v0, v29
	v_mul_f32_e32 v0, v17, v23
	v_fma_f32 v17, v2, v0, v30
	v_mul_f32_e32 v0, v16, v23
	s_waitcnt vmcnt(0)
	v_fma_f32 v24, v24, v36, v32
	v_fma_f32 v22, v25, v22, v33
	v_fma_f32 v21, v26, v21, v34
	v_fmac_f32_e32 v35, v27, v20
	v_fmac_f32_e32 v31, v3, v0
	v_cvt_pk_bf16_f32 v0, v24, v22
	v_cvt_pk_bf16_f32 v1, v21, v35
	v_cvt_pk_bf16_f32 v2, v19, v18
	v_cvt_pk_bf16_f32 v3, v17, v31
	ds_write_b128 v107, v[0:3] offset:32
	v_mov_b32_e32 v0, v202
	v_mov_b32_e32 v1, v203
	v_mov_b32_e32 v2, v204
	v_mov_b32_e32 v3, v205
	v_mov_b32_e32 v16, v206
	v_mov_b32_e32 v17, v207
	v_mov_b32_e32 v18, v208
	v_mov_b32_e32 v19, v209
	v_mov_b32_e32 v24, v210
	v_mov_b32_e32 v25, v211
	v_mov_b32_e32 v26, v212
	v_mov_b32_e32 v27, v213
	s_nop 0
	v_mov_b32_e32 v6, v214
	v_mov_b32_e32 v7, v215
	v_mov_b32_e32 v8, v216
	v_mov_b32_e32 v9, v217
	v_mov_b32_e32 v32, v105
	v_mov_b32_e32 v33, v104
	v_mov_b32_e32 v34, v103
	s_waitcnt vmcnt(1)
	v_fma_f32 v11, v11, v0, v24
	v_mul_f32_e32 v0, v10, v23
	v_fma_f32 v10, v0, v1, v25
	v_mul_f32_e32 v0, v5, v23
	v_fma_f32 v5, v0, v2, v26
	v_mul_f32_e32 v0, v4, v23
	s_waitcnt vmcnt(0)
	v_fma_f32 v6, v16, v15, v6
	v_fma_f32 v7, v17, v14, v7
	v_fma_f32 v8, v18, v13, v8
	v_fmac_f32_e32 v9, v12, v19
	v_fmac_f32_e32 v27, v0, v3
	v_cvt_pk_bf16_f32 v0, v6, v7
	v_cvt_pk_bf16_f32 v1, v8, v9
	v_cvt_pk_bf16_f32 v2, v11, v10
	v_cvt_pk_bf16_f32 v3, v5, v27
	ds_write_b128 v107, v[0:3] offset:48
	v_readlane_b32 s98, v254, 8
	s_nop 0
	s_and_b32 s99, s98, 3
	s_sub_i32 s98, s33, s98
	s_cmp_lg_u32 s99, 0
	s_cbranch_scc1 .Lsg_stage_w
	s_cmpk_gt_i32 s98, 0x7ff
	s_cbranch_scc1 .Lsg_skip_w
